# gmlp: Wm/bias hoisted, u prefetched one item ahead, item-head wait counted (vmcnt 8) so output stores stay in flight
# speedup vs baseline: 1.0011x; 1.0011x over previous
; #define LAS __attribute__((address_space(3)))
; __device__ __forceinline__ int fresh_tid() { int t = threadIdx.x; asm volatile("" : "+v"(t)); return t; }
; __device__ __forceinline__ void gmlp_phase(LAS unsigned char* lds, int it0, int G, const bf16_t* Wm, const bf16_t* Vt, const bf16_t* U, const float* bs, bf16_t* YAB) {
;     const int tid = fresh_tid(), lane = tid & 63, wid = __builtin_amdgcn_readfirstlane(tid >> 6), fr = lane & 15, fq = lane >> 4;
;     constexpr int NIT = 1024 + 32;
;     u32x4 st[4];
;     ...
;     int item = it0;
;     if (item < NIT) GM_LOAD(item);
;     for (; item < NIT; item += G) {
;         const bool samp = item >= 1024; const int g = item & 3;
;         const int tok0 = samp ? MP + 64 * ((item - 1024) >> 2) : 128 * (item >> 2);
;         const bool active = !(samp && wid >= 4);
;         const int nk = (samp || wid < 4) ? 2 : 4;
;         const int row = tok0 + 16 * wid + fr;
;         bf16x8 bfr[4]; u32x2 uu8[8]; float bias = 0.f;
;         if (active) {
;             const bf16_t* wrow = Wm + (size_t)(g * 128 + 16 * wid + fr) * 128 + 8 * fq;
; #pragma unroll
;             for (int kk = 0; kk < 4; ++kk) bfr[kk] = *(const bf16x8*)(wrow + 32 * kk);
; #pragma unroll
;             for (int n = 0; n < 8; ++n) uu8[n] = __builtin_nontemporal_load((const u32x2*)(U + (size_t)row * 512 + 128 * g + 16 * n + 4 * fq));
;             bias = bs[g * 128 + 16 * wid + fr];
.LBB0_675:
	s_ashr_i32 s6, s6, 6
	s_cmp_gt_i32 s6, 3
	v_bfe_u32 v13, v20, 4, 2
	s_cselect_b64 s[0:1], -1, 0
	s_cmp_lt_i32 s6, 4
	v_lshl_or_b32 v69, s6, 4, v21
	v_mov_b32_e32 v12, 0
	v_readlane_b32 s6, v238, 36
	v_lshlrev_b32_e32 v18, 4, v13
	v_mov_b32_e32 v19, v12
	v_readlane_b32 s7, v238, 37
	v_lshlrev_b32_e32 v22, 4, v21
	v_mov_b32_e32 v23, v12
	v_lshl_add_u64 v[66:67], s[6:7], 0, v[18:19]
	v_readlane_b32 s6, v238, 51
	v_readlane_b32 s7, v238, 52
	v_lshlrev_b32_e32 v68, 2, v13
	v_lshlrev_b32_e32 v13, 4, v20
	v_lshl_add_u64 v[70:71], s[6:7], 0, v[22:23]
	v_ashrrev_i32_e32 v92, 4, v20
	v_add_u32_e32 v22, 0x200, v20
	v_add_u32_e32 v23, 0x400, v20
	v_add_u32_e32 v20, 0x600, v20
	v_and_b32_e32 v13, 0xf0, v13
	s_movk_i32 s7, 0x110
	v_ashrrev_i32_e32 v93, 4, v22
	v_ashrrev_i32_e32 v94, 4, v23
	v_ashrrev_i32_e32 v95, 4, v20
	v_add_u32_e32 v13, 0, v13
	v_cmp_gt_u32_e64 s[48:49], 8, v21
	v_mad_u32_u24 v19, v21, s7, 0
	s_cselect_b32 s6, 2, 4
	v_mul_lo_u32 v21, v92, s7
	v_mul_lo_u32 v22, v93, s7
	v_mul_lo_u32 v23, v94, s7
	v_mul_lo_u32 v20, v95, s7
	s_add_i32 s10, s3, s34
	s_mov_b32 s41, 0
	s_lshl_b32 s7, s3, 5
	s_lshl_b32 s21, s34, 5
	s_lshl_b32 s22, s3, 4
	s_lshl_b32 s23, s34, 4
	s_lshl_b32 s24, s10, 7
	s_lshl_b32 s25, s34, 7
	v_add_u32_e32 v96, v13, v21
	v_add_u32_e32 v97, v13, v22
	v_add_u32_e32 v98, v13, v23
	v_add_u32_e32 v99, v13, v20
	s_mov_b32 s26, 0x10400
	v_add_u32_e32 v100, v19, v18
	s_and_b32 s27, s3, 3
	v_lshl_add_u32 v34, s27, 7, v69
	v_ashrrev_i32_e32 v35, 31, v34
	v_lshlrev_b64 v[142:143], 8, v[34:35]
	v_lshl_add_u64 v[142:143], v[66:67], 0, v[142:143]
	global_load_dwordx4 v[30:33], v[142:143], off
	global_load_dwordx4 v[26:29], v[142:143], off offset:64
	global_load_dwordx4 v[22:25], v[142:143], off offset:128
	global_load_dwordx4 v[18:21], v[142:143], off offset:192
	v_lshl_add_u64 v[142:143], v[34:35], 2, s[58:59]
	global_load_dword v162, v[142:143], off
	s_lshl_b32 s98, s3, 5
	s_and_b32 s98, s98, 0xffffff80
	s_lshl_b32 s99, s3, 4
	s_and_b32 s99, s99, 0x7fffffc0
	s_add_i32 s99, s99, 0x4000
	s_cmpk_lt_i32 s3, 0x400
	s_cselect_b32 s98, s98, s99
	s_cbranch_scc1 .Lgm_u0_go
	s_and_b64 vcc, exec, s[0:1]
	s_cbranch_vccnz .Lgm_u0_skip
.Lgm_u0_go:
	v_add_u32_e32 v160, s98, v69
	v_ashrrev_i32_e32 v161, 31, v160
	v_lshlrev_b64 v[160:161], 10, v[160:161]
	v_lshl_add_u64 v[160:161], s[16:17], 0, v[160:161]
	s_and_b32 s100, s3, 3
	s_lshl_b32 s100, s100, 8
	s_mov_b32 s101, 0
	v_lshl_add_u64 v[160:161], v[160:161], 0, s[100:101]
	v_lshlrev_b32_e32 v164, 1, v68
	v_mov_b32_e32 v165, 0
	v_lshl_add_u64 v[160:161], v[160:161], 0, v[164:165]
	global_load_dwordx2 v[158:159], v[160:161], off nt
	global_load_dwordx2 v[156:157], v[160:161], off offset:32 nt
	global_load_dwordx2 v[154:155], v[160:161], off offset:64 nt
	global_load_dwordx2 v[152:153], v[160:161], off offset:96 nt
	global_load_dwordx2 v[150:151], v[160:161], off offset:128 nt
	global_load_dwordx2 v[148:149], v[160:161], off offset:160 nt
	global_load_dwordx2 v[146:147], v[160:161], off offset:192 nt
	global_load_dwordx2 v[144:145], v[160:161], off offset:224 nt
.Lgm_u0_skip:
	s_mov_b32 s98, 0
	s_branch .LBB0_678
; __device__ __forceinline__ unsigned cvt_pk_bf16(float lo, float hi) { unsigned r; asm("v_cvt_pk_bf16_f32 %0, %1, %2" : "=v"(r) : "v"(lo), "v"(hi)); return r; }
; __device__ __forceinline__ void gmlp_phase(LAS unsigned char* lds, int it0, int G, const bf16_t* Wm, const bf16_t* Vt, const bf16_t* U, const float* bs, bf16_t* YAB) {
;     ...
; #pragma unroll
;             for (int n = 0; n < 8; ++n) { const int col = 128 * g + 16 * n + 4 * fq; const u32x2 uu = uu8[n];
;                 const float y0 = __uint_as_float(uu.x << 16) * (acc[n][0] + bias), y1 = __uint_as_float(uu.x & 0xffff0000u) * (acc[n][1] + bias);
;                 const float y2 = __uint_as_float(uu.y << 16) * (acc[n][2] + bias), y3 = __uint_as_float(uu.y & 0xffff0000u) * (acc[n][3] + bias);
;                 u32x2 w; w.x = cvt_pk_bf16(y0, y1); w.y = cvt_pk_bf16(y2, y3);
;                 *(u32x2*)(YAB + (size_t)row * DM + col) = w; }
.LBB0_676:
	v_lshlrev_b32_e32 v13, 16, v86
	v_add_f32_e32 v62, v162, v62
	v_mul_f32_e32 v13, v62, v13
	v_and_b32_e32 v62, 0xffff0000, v86
	v_add_f32_e32 v63, v162, v63
	v_mul_f32_e32 v62, v63, v62
	v_cvt_pk_bf16_f32 v62, v13, v62
	v_lshlrev_b32_e32 v13, 16, v84
	v_add_f32_e32 v58, v162, v58
	v_mul_f32_e32 v13, v58, v13
	v_and_b32_e32 v58, 0xffff0000, v84
	v_add_f32_e32 v59, v162, v59
	v_mul_f32_e32 v58, v59, v58
	v_cvt_pk_bf16_f32 v58, v13, v58
	v_lshlrev_b32_e32 v13, 16, v82
	v_add_f32_e32 v54, v162, v54
	v_mul_f32_e32 v13, v54, v13
	v_and_b32_e32 v54, 0xffff0000, v82
	v_add_f32_e32 v55, v162, v55
	v_mul_f32_e32 v54, v55, v54
	v_cvt_pk_bf16_f32 v54, v13, v54
	v_lshlrev_b32_e32 v13, 16, v80
	v_add_f32_e32 v50, v162, v50
	v_mul_f32_e32 v13, v50, v13
	v_and_b32_e32 v50, 0xffff0000, v80
	v_add_f32_e32 v51, v162, v51
	v_mul_f32_e32 v50, v51, v50
	v_cvt_pk_bf16_f32 v50, v13, v50
	v_lshlrev_b32_e32 v13, 16, v78
	v_add_f32_e32 v46, v162, v46
	v_mul_f32_e32 v13, v46, v13
	v_and_b32_e32 v46, 0xffff0000, v78
	v_add_f32_e32 v47, v162, v47
	v_mul_f32_e32 v46, v47, v46
	v_cvt_pk_bf16_f32 v46, v13, v46
	v_lshlrev_b32_e32 v13, 16, v76
	v_add_f32_e32 v42, v162, v42
	v_mul_f32_e32 v13, v42, v13
	v_and_b32_e32 v42, 0xffff0000, v76
	v_add_f32_e32 v43, v162, v43
	v_mul_f32_e32 v42, v43, v42
	v_cvt_pk_bf16_f32 v42, v13, v42
	v_lshlrev_b32_e32 v13, 16, v74
	v_add_f32_e32 v38, v162, v38
	v_mul_f32_e32 v13, v38, v13
	v_and_b32_e32 v38, 0xffff0000, v74
	v_add_f32_e32 v39, v162, v39
	v_lshlrev_b32_e32 v63, 16, v87
	v_add_f32_e32 v64, v162, v64
	v_mul_f32_e32 v38, v39, v38
	v_mul_f32_e32 v63, v64, v63
	v_and_b32_e32 v64, 0xffff0000, v87
	v_add_f32_e32 v65, v162, v65
	v_cvt_pk_bf16_f32 v38, v13, v38
	v_lshlrev_b32_e32 v13, 16, v72
	v_add_f32_e32 v34, v162, v34
	v_lshlrev_b64 v[90:91], 11, v[90:91]
	v_mul_f32_e32 v64, v65, v64
	v_mul_f32_e32 v13, v34, v13
	v_and_b32_e32 v34, 0xffff0000, v72
	v_add_f32_e32 v35, v162, v35
	v_lshl_add_u64 v[90:91], s[8:9], 0, v[90:91]
	v_cvt_pk_bf16_f32 v63, v63, v64
	v_lshl_or_b32 v64, s27, 8, v88
	v_mov_b32_e32 v65, v12
	v_lshlrev_b32_e32 v59, 16, v85
	v_add_f32_e32 v60, v162, v60
	v_lshlrev_b32_e32 v55, 16, v83
	v_add_f32_e32 v56, v162, v56
	v_lshlrev_b32_e32 v51, 16, v81
	v_add_f32_e32 v52, v162, v52
	v_lshlrev_b32_e32 v47, 16, v79
	v_add_f32_e32 v48, v162, v48
	v_lshlrev_b32_e32 v43, 16, v77
	v_add_f32_e32 v44, v162, v44
	v_lshlrev_b32_e32 v39, 16, v75
	v_add_f32_e32 v40, v162, v40
	v_mul_f32_e32 v34, v35, v34
	v_lshlrev_b32_e32 v35, 16, v73
	v_add_f32_e32 v36, v162, v36
	v_lshl_add_u64 v[64:65], v[90:91], 0, v[64:65]
	v_mul_f32_e32 v59, v60, v59
	v_and_b32_e32 v60, 0xffff0000, v85
	v_add_f32_e32 v61, v162, v61
	v_mul_f32_e32 v55, v56, v55
	v_and_b32_e32 v56, 0xffff0000, v83
	v_add_f32_e32 v57, v162, v57
	v_mul_f32_e32 v51, v52, v51
	v_and_b32_e32 v52, 0xffff0000, v81
	v_add_f32_e32 v53, v162, v53
	v_mul_f32_e32 v47, v48, v47
	v_and_b32_e32 v48, 0xffff0000, v79
	v_add_f32_e32 v49, v162, v49
	v_mul_f32_e32 v43, v44, v43
	v_and_b32_e32 v44, 0xffff0000, v77
	v_add_f32_e32 v45, v162, v45
	v_mul_f32_e32 v39, v40, v39
	v_and_b32_e32 v40, 0xffff0000, v75
	v_add_f32_e32 v41, v162, v41
	v_mul_f32_e32 v35, v36, v35
	v_and_b32_e32 v36, 0xffff0000, v73
	v_add_f32_e32 v37, v162, v37
	global_store_dwordx2 v[64:65], v[62:63], off
	v_mul_f32_e32 v60, v61, v60
	v_cvt_pk_bf16_f32 v59, v59, v60
	global_store_dwordx2 v[64:65], v[58:59], off offset:32
	v_mul_f32_e32 v56, v57, v56
	v_cvt_pk_bf16_f32 v55, v55, v56
	global_store_dwordx2 v[64:65], v[54:55], off offset:64
	v_mul_f32_e32 v52, v53, v52
	v_cvt_pk_bf16_f32 v51, v51, v52
	global_store_dwordx2 v[64:65], v[50:51], off offset:96
	v_mul_f32_e32 v48, v49, v48
	v_cvt_pk_bf16_f32 v47, v47, v48
	global_store_dwordx2 v[64:65], v[46:47], off offset:128
	v_mul_f32_e32 v44, v45, v44
	v_cvt_pk_bf16_f32 v43, v43, v44
	global_store_dwordx2 v[64:65], v[42:43], off offset:160
	v_mul_f32_e32 v40, v41, v40
	v_cvt_pk_bf16_f32 v39, v39, v40
	global_store_dwordx2 v[64:65], v[38:39], off offset:192
	v_mul_f32_e32 v36, v37, v36
	v_cvt_pk_bf16_f32 v34, v13, v34
	v_cvt_pk_bf16_f32 v35, v35, v36
	global_store_dwordx2 v[64:65], v[34:35], off offset:224
	s_mov_b32 s98, 1

; #define LAS __attribute__((address_space(3)))
; __device__ __forceinline__ void gmlp_phase(LAS unsigned char* lds, int it0, int G, const bf16_t* Wm, const bf16_t* Vt, const bf16_t* U, const float* bs, bf16_t* YAB) {
;     ...
;     int item = it0;
;     if (item < NIT) GM_LOAD(item);
;     for (; item < NIT; item += G) {
;         const bool samp = item >= 1024; const int g = item & 3;
;         const int tok0 = samp ? MP + 64 * ((item - 1024) >> 2) : 128 * (item >> 2);
;         const bool active = !(samp && wid >= 4);
;         const int nk = (samp || wid < 4) ? 2 : 4;
;         const int row = tok0 + 16 * wid + fr;
;         bf16x8 bfr[4]; u32x2 uu8[8]; float bias = 0.f;
;         if (active) {
;             const bf16_t* wrow = Wm + (size_t)(g * 128 + 16 * wid + fr) * 128 + 8 * fq;
; #pragma unroll
;             for (int kk = 0; kk < 4; ++kk) bfr[kk] = *(const bf16x8*)(wrow + 32 * kk);
; #pragma unroll
;             for (int n = 0; n < 8; ++n) uu8[n] = __builtin_nontemporal_load((const u32x2*)(U + (size_t)row * 512 + 128 * g + 16 * n + 4 * fq));
;             bias = bs[g * 128 + 16 * wid + fr];
;         }
; #pragma unroll
;         for (int q = 0; q < 4; ++q) { const int c = tid + 512 * q; *(LAS u32x4*)(lds + (c >> 4) * GM_PITCH + (c & 15) * 16) = st[q]; }
;         __syncthreads();
;         if (item + G < NIT) GM_LOAD(item + G);
.LBB0_684:
	s_add_i32 s3, s3, s34
	s_cmpk_gt_i32 s3, 0x41f
	s_cselect_b64 s[44:45], -1, 0
	s_and_b64 vcc, exec, s[44:45]
	s_cmp_eq_u32 s98, 1
	s_cbranch_scc1 .Lgm_w8
	s_waitcnt vmcnt(0)
	s_branch .Lgm_wd
.Lgm_w8:
	s_waitcnt vmcnt(8)
.Lgm_wd:
	v_mov_b64_e32 v[72:73], v[144:145]
	v_mov_b64_e32 v[74:75], v[146:147]
	v_mov_b64_e32 v[76:77], v[148:149]
	v_mov_b64_e32 v[78:79], v[150:151]
	v_mov_b64_e32 v[80:81], v[152:153]
	v_mov_b64_e32 v[82:83], v[154:155]
	v_mov_b64_e32 v[84:85], v[156:157]
	v_mov_b64_e32 v[86:87], v[158:159]
	ds_write_b128 v96, v[0:3]
	ds_write_b128 v97, v[4:7]
	ds_write_b128 v98, v[8:11]
	ds_write_b128 v99, v[14:17]
	s_waitcnt lgkmcnt(0)
	s_barrier
	s_cbranch_vccnz .LBB0_698
	s_lshl_b32 s98, s3, 5
	s_and_b32 s98, s98, 0xffffff80
	s_lshl_b32 s99, s3, 4
	s_and_b32 s99, s99, 0x7fffffc0
	s_add_i32 s99, s99, 0x4000
	s_cmpk_lt_i32 s3, 0x400
	s_cselect_b32 s98, s98, s99
	s_cbranch_scc1 .Lgm_u1_go
	s_and_b64 vcc, exec, s[0:1]
	s_cbranch_vccnz .Lgm_u1_skip

; __device__ __forceinline__ void gmlp_phase(LAS unsigned char* lds, int it0, int G, const bf16_t* Wm, const bf16_t* Vt, const bf16_t* U, const float* bs, bf16_t* YAB) {
;     ...
;         if (item + G < NIT) GM_LOAD(item + G);
.Lgm_u1_skip:
	s_cmpk_lt_i32 s3, 0x400
	s_mov_b64 s[10:11], -1
	s_cbranch_scc1 .LBB0_687
	s_add_i32 s10, s23, s22
	s_and_b32 s10, s10, 0x7fffffc0
	s_add_i32 s52, s10, 0x4000
	s_mov_b64 s[10:11], 0

; #define LAS __attribute__((address_space(3)))
; __device__ __forceinline__ void gmlp_phase(LAS unsigned char* lds, int it0, int G, const bf16_t* Wm, const bf16_t* Vt, const bf16_t* U, const float* bs, bf16_t* YAB) {
;     ...
;         if (active) {
;             f32x4 acc[8];
; #pragma unroll
;             for (int n = 0; n < 8; ++n) acc[n] = (f32x4){0.f, 0.f, 0.f, 0.f};
;             const LAS unsigned char* ab = lds + fr * GM_PITCH + fq * 16;
; #pragma unroll
;             for (int kk = 0; kk < 4; ++kk) { if (kk < nk) {
; #pragma unroll
;                 for (int n = 0; n < 8; ++n) { const bf16x8 afr = *(const LAS bf16x8*)(ab + (16 * n) * GM_PITCH + kk * 64);
;                     acc[n] = __builtin_amdgcn_mfma_f32_16x16x32_bf16(afr, bfr[kk], acc[n], 0, 0, 0); } } }
.LBB0_698:
	s_xor_b64 s[10:11], s[50:51], -1
	s_andn2_b64 vcc, exec, s[10:11]
	s_mov_b32 s98, 0
	s_cbranch_vccnz .LBB0_677
	ds_read_b128 v[34:37], v100
	ds_read_b128 v[38:41], v100 offset:64
	ds_read_b128 v[42:45], v100 offset:4352
	ds_read_b128 v[46:49], v100 offset:4416
	ds_read_b128 v[50:53], v100 offset:8704
	ds_read_b128 v[54:57], v100 offset:8768
	ds_read_b128 v[58:61], v100 offset:13056
	ds_read_b128 v[102:105], v100 offset:13120
	s_waitcnt lgkmcnt(1)
	v_mfma_f32_16x16x32_bf16 v[106:109], v[58:61], v[30:33], 0
	ds_read_b128 v[58:61], v100 offset:17408
	ds_read_b128 v[110:113], v100 offset:17472
	s_cmp_lt_u32 s33, 3
	s_waitcnt lgkmcnt(1)
	v_mfma_f32_16x16x32_bf16 v[114:117], v[58:61], v[30:33], 0
	ds_read_b128 v[58:61], v100 offset:21760
	ds_read_b128 v[118:121], v100 offset:21824
	s_waitcnt lgkmcnt(1)
	v_mfma_f32_16x16x32_bf16 v[122:125], v[58:61], v[30:33], 0
	ds_read_b128 v[58:61], v100 offset:26112
	ds_read_b128 v[126:129], v100 offset:26176
	s_waitcnt lgkmcnt(1)
	v_mfma_f32_16x16x32_bf16 v[130:133], v[58:61], v[30:33], 0
	ds_read_b128 v[58:61], v100 offset:30464
	ds_read_b128 v[134:137], v100 offset:30528
	v_mfma_f32_16x16x32_bf16 v[34:37], v[34:37], v[30:33], 0
	v_mfma_f32_16x16x32_bf16 v[42:45], v[42:45], v[30:33], 0
	v_mfma_f32_16x16x32_bf16 v[50:53], v[50:53], v[30:33], 0
	s_waitcnt lgkmcnt(1)
	v_mfma_f32_16x16x32_bf16 v[138:141], v[58:61], v[30:33], 0
	v_mfma_f32_16x16x32_bf16 v[62:65], v[38:41], v[26:29], v[34:37]
	v_mfma_f32_16x16x32_bf16 v[58:61], v[46:49], v[26:29], v[42:45]
	v_mfma_f32_16x16x32_bf16 v[54:57], v[54:57], v[26:29], v[50:53]
	v_mfma_f32_16x16x32_bf16 v[50:53], v[102:105], v[26:29], v[106:109]
	v_mfma_f32_16x16x32_bf16 v[46:49], v[110:113], v[26:29], v[114:117]
	v_mfma_f32_16x16x32_bf16 v[42:45], v[118:121], v[26:29], v[122:125]
	v_mfma_f32_16x16x32_bf16 v[38:41], v[126:129], v[26:29], v[130:133]
	s_waitcnt lgkmcnt(0)
	v_mfma_f32_16x16x32_bf16 v[34:37], v[134:137], v[26:29], v[138:141]
	s_cbranch_scc1 .LBB0_701
	ds_read_b128 v[102:105], v100 offset:128
	ds_read_b128 v[106:109], v100 offset:4480
	s_waitcnt lgkmcnt(1)
	v_mfma_f32_16x16x32_bf16 v[62:65], v[102:105], v[22:25], v[62:65]
	ds_read_b128 v[102:105], v100 offset:8832
	s_waitcnt lgkmcnt(1)
	v_mfma_f32_16x16x32_bf16 v[58:61], v[106:109], v[22:25], v[58:61]
	ds_read_b128 v[106:109], v100 offset:13184
	s_waitcnt lgkmcnt(1)
	v_mfma_f32_16x16x32_bf16 v[54:57], v[102:105], v[22:25], v[54:57]
	ds_read_b128 v[102:105], v100 offset:17536
	s_waitcnt lgkmcnt(1)
	v_mfma_f32_16x16x32_bf16 v[50:53], v[106:109], v[22:25], v[50:53]
	ds_read_b128 v[106:109], v100 offset:21888
	s_waitcnt lgkmcnt(1)
	v_mfma_f32_16x16x32_bf16 v[46:49], v[102:105], v[22:25], v[46:49]
	ds_read_b128 v[102:105], v100 offset:26240
	s_waitcnt lgkmcnt(1)
	v_mfma_f32_16x16x32_bf16 v[42:45], v[106:109], v[22:25], v[42:45]
	ds_read_b128 v[106:109], v100 offset:30592
	s_waitcnt lgkmcnt(1)
	v_mfma_f32_16x16x32_bf16 v[38:41], v[102:105], v[22:25], v[38:41]
	s_waitcnt lgkmcnt(0)
	v_mfma_f32_16x16x32_bf16 v[34:37], v[106:109], v[22:25], v[34:37]
